# attention epilogue (7.3): chunk pairs exchanged across half-waves with v_permlane32_swap, 4 dwordx4 stores per lane instead of 8 dwordx2
# speedup vs baseline: 1.0148x; 1.0011x over previous
; __device__ __forceinline__ unsigned pk2(float lo, float hi) { f32x2_t v = {lo, hi}; bf16x2_t b = __builtin_convertvector(v, bf16x2_t); return __builtin_bit_cast(unsigned, b); }
; __device__ __forceinline__ float bflo(unsigned v) { return __uint_as_float(v << 16); }
; __device__ __forceinline__ float bfhi(unsigned v) { return __uint_as_float(v & 0xffff0000u); }
; __device__ void attn_item(const Params& p, char* lds, int bh, int qi) {
;     ...
;   lsum += __shfl_xor(lsum, 32);
;   const float inv = __builtin_amdgcn_rcpf(lsum);
;   const int b = bh >> 3, hd = bh & 7;
;   const size_t tok = (size_t)b * SEQ + qpos;
;   const u16* ga = p.GA + tok * 512 + hd * 64;
;   u16* yo = p.Ymix + tok * 1024 + hd * 64;
; #pragma unroll
;   for (int d = 0; d < 2; ++d)
; #pragma unroll
;     for (int rq = 0; rq < 4; ++rq) {
;       const int c = d * 32 + 8 * rq + 4 * h;
;       const u32x2 g = *(const u32x2*)(ga + c);
;       u32x2 w;
;       w.x = pk2(O[d][rq * 4 + 0] * inv * bflo(g.x), O[d][rq * 4 + 1] * inv * bfhi(g.x));
;       w.y = pk2(O[d][rq * 4 + 2] * inv * bflo(g.y), O[d][rq * 4 + 3] * inv * bfhi(g.y));
;       *(u32x2*)(yo + c) = w;
;     }
.LBB0_392:
	v_lshl_add_u32 v94, s36, 9, v94
	v_lshlrev_b64 v[34:35], 10, v[94:95]
	v_lshl_add_u64 v[34:35], v[98:99], 0, v[34:35]
	global_load_dwordx2 v[44:45], v[34:35], off
	global_load_dwordx2 v[46:47], v[34:35], off offset:16
	global_load_dwordx2 v[48:49], v[34:35], off offset:32
	global_load_dwordx2 v[50:51], v[34:35], off offset:48
	global_load_dwordx2 v[52:53], v[34:35], off offset:64
	global_load_dwordx2 v[54:55], v[34:35], off offset:80
	global_load_dwordx2 v[56:57], v[34:35], off offset:96
	global_load_dwordx2 v[58:59], v[34:35], off offset:112
	v_cmp_lt_i32_e32 vcc, v156, v157
	v_lshlrev_b64 v[40:41], 11, v[94:95]
	v_lshl_add_u64 v[40:41], v[100:101], 0, v[40:41]
	v_cndmask_b32_e32 v38, v1, v156, vcc
	v_lshlrev_b32_e32 v38, 2, v38
	ds_bpermute_b32 v38, v38, v126
	v_mbcnt_lo_u32_b32 v36, -1, 0
	v_mbcnt_hi_u32_b32 v36, -1, v36
	v_and_b32_e32 v36, 32, v36
	v_lshrrev_b32_e32 v36, 2, v36
	v_mov_b32_e32 v37, 0
	v_lshl_add_u64 v[40:41], v[40:41], 0, v[36:37]
	s_mov_b64 s[4:5], 0
	s_waitcnt lgkmcnt(0)
	v_add_f32_e32 v38, v126, v38
	v_rcp_f32_e32 v38, v38
	s_nop 0
	s_waitcnt vmcnt(7)
	v_lshlrev_b32_e32 v42, 16, v44
	v_and_b32_e32 v43, 0xffff0000, v44
	v_lshlrev_b32_e32 v36, 16, v45
	v_and_b32_e32 v37, 0xffff0000, v45
	v_pk_mul_f32 v[18:19], v[18:19], v[38:39] op_sel_hi:[1,0]
	v_pk_mul_f32 v[20:21], v[20:21], v[38:39] op_sel_hi:[1,0]
	v_pk_mul_f32 v[18:19], v[18:19], v[42:43]
	v_pk_mul_f32 v[20:21], v[20:21], v[36:37]
	v_cvt_pk_bf16_f32 v60, v18, v19
	v_cvt_pk_bf16_f32 v61, v20, v21
	s_waitcnt vmcnt(6)
	v_lshlrev_b32_e32 v42, 16, v46
	v_and_b32_e32 v43, 0xffff0000, v46
	v_lshlrev_b32_e32 v36, 16, v47
	v_and_b32_e32 v37, 0xffff0000, v47
	v_pk_mul_f32 v[22:23], v[22:23], v[38:39] op_sel_hi:[1,0]
	v_pk_mul_f32 v[24:25], v[24:25], v[38:39] op_sel_hi:[1,0]
	v_pk_mul_f32 v[22:23], v[22:23], v[42:43]
	v_pk_mul_f32 v[24:25], v[24:25], v[36:37]
	v_cvt_pk_bf16_f32 v62, v22, v23
	v_cvt_pk_bf16_f32 v63, v24, v25
	s_nop 1
	v_permlane32_swap_b32_e32 v60, v62
	v_permlane32_swap_b32_e32 v61, v63
	global_store_dwordx4 v[40:41], v[60:63], off
	s_waitcnt vmcnt(6)
	v_lshlrev_b32_e32 v42, 16, v48
	v_and_b32_e32 v43, 0xffff0000, v48
	v_lshlrev_b32_e32 v36, 16, v49
	v_and_b32_e32 v37, 0xffff0000, v49
	v_pk_mul_f32 v[26:27], v[26:27], v[38:39] op_sel_hi:[1,0]
	v_pk_mul_f32 v[28:29], v[28:29], v[38:39] op_sel_hi:[1,0]
	v_pk_mul_f32 v[26:27], v[26:27], v[42:43]
	v_pk_mul_f32 v[28:29], v[28:29], v[36:37]
	v_cvt_pk_bf16_f32 v64, v26, v27
	v_cvt_pk_bf16_f32 v65, v28, v29
	s_waitcnt vmcnt(5)
	v_lshlrev_b32_e32 v42, 16, v50
	v_and_b32_e32 v43, 0xffff0000, v50
	v_lshlrev_b32_e32 v36, 16, v51
	v_and_b32_e32 v37, 0xffff0000, v51
	v_pk_mul_f32 v[30:31], v[30:31], v[38:39] op_sel_hi:[1,0]
	v_pk_mul_f32 v[32:33], v[32:33], v[38:39] op_sel_hi:[1,0]
	v_pk_mul_f32 v[30:31], v[30:31], v[42:43]
	v_pk_mul_f32 v[32:33], v[32:33], v[36:37]
	v_cvt_pk_bf16_f32 v66, v30, v31
	v_cvt_pk_bf16_f32 v67, v32, v33
	s_nop 1
	v_permlane32_swap_b32_e32 v64, v66
	v_permlane32_swap_b32_e32 v65, v67
	global_store_dwordx4 v[40:41], v[64:67], off offset:32
	s_waitcnt vmcnt(5)
	v_lshlrev_b32_e32 v42, 16, v52
	v_and_b32_e32 v43, 0xffff0000, v52
	v_lshlrev_b32_e32 v36, 16, v53
	v_and_b32_e32 v37, 0xffff0000, v53
	v_pk_mul_f32 v[2:3], v[2:3], v[38:39] op_sel_hi:[1,0]
	v_pk_mul_f32 v[4:5], v[4:5], v[38:39] op_sel_hi:[1,0]
	v_pk_mul_f32 v[2:3], v[2:3], v[42:43]
	v_pk_mul_f32 v[4:5], v[4:5], v[36:37]
	v_cvt_pk_bf16_f32 v68, v2, v3
	v_cvt_pk_bf16_f32 v69, v4, v5
	s_waitcnt vmcnt(4)
	v_lshlrev_b32_e32 v42, 16, v54
	v_and_b32_e32 v43, 0xffff0000, v54
	v_lshlrev_b32_e32 v36, 16, v55
	v_and_b32_e32 v37, 0xffff0000, v55
	v_pk_mul_f32 v[6:7], v[6:7], v[38:39] op_sel_hi:[1,0]
	v_pk_mul_f32 v[8:9], v[8:9], v[38:39] op_sel_hi:[1,0]
	v_pk_mul_f32 v[6:7], v[6:7], v[42:43]
	v_pk_mul_f32 v[8:9], v[8:9], v[36:37]
	v_cvt_pk_bf16_f32 v70, v6, v7
	v_cvt_pk_bf16_f32 v71, v8, v9
	s_nop 1
	v_permlane32_swap_b32_e32 v68, v70
	v_permlane32_swap_b32_e32 v69, v71
	global_store_dwordx4 v[40:41], v[68:71], off offset:64
	s_waitcnt vmcnt(4)
	v_lshlrev_b32_e32 v42, 16, v56
	v_and_b32_e32 v43, 0xffff0000, v56
	v_lshlrev_b32_e32 v36, 16, v57
	v_and_b32_e32 v37, 0xffff0000, v57
	v_pk_mul_f32 v[10:11], v[10:11], v[38:39] op_sel_hi:[1,0]
	v_pk_mul_f32 v[12:13], v[12:13], v[38:39] op_sel_hi:[1,0]
	v_pk_mul_f32 v[10:11], v[10:11], v[42:43]
	v_pk_mul_f32 v[12:13], v[12:13], v[36:37]
	v_cvt_pk_bf16_f32 v72, v10, v11
	v_cvt_pk_bf16_f32 v73, v12, v13
	s_waitcnt vmcnt(3)
	v_lshlrev_b32_e32 v42, 16, v58
	v_and_b32_e32 v43, 0xffff0000, v58
	v_lshlrev_b32_e32 v36, 16, v59
	v_and_b32_e32 v37, 0xffff0000, v59
	v_pk_mul_f32 v[14:15], v[14:15], v[38:39] op_sel_hi:[1,0]
	v_pk_mul_f32 v[16:17], v[16:17], v[38:39] op_sel_hi:[1,0]
	v_pk_mul_f32 v[14:15], v[14:15], v[42:43]
	v_pk_mul_f32 v[16:17], v[16:17], v[36:37]
	v_cvt_pk_bf16_f32 v74, v14, v15
	v_cvt_pk_bf16_f32 v75, v16, v17
	s_nop 1
	v_permlane32_swap_b32_e32 v72, v74
	v_permlane32_swap_b32_e32 v73, v75
	global_store_dwordx4 v[40:41], v[72:75], off offset:96
